# weight-prep split: phase 0 of layers 1-3 converts items <4096 only; workgroups 128-255 convert the rest (ff1 tail + ff2) in their idle slot after phase 1
# baseline (speedup 1.0000x reference)
; #define LAS __attribute__((address_space(3)))
; __device__ __forceinline__ unsigned xb_ld(unsigned* p)              { return __hip_atomic_load(p, __ATOMIC_RELAXED, __HIP_MEMORY_SCOPE_AGENT); }
; __device__ __forceinline__ unsigned xb_add(unsigned* p, unsigned v) { return __hip_atomic_fetch_add(p, v, __ATOMIC_RELAXED, __HIP_MEMORY_SCOPE_AGENT); }
; __device__ __forceinline__ unsigned xb_xcc_id() { return (unsigned)__builtin_amdgcn_s_getreg((3 << 11) | 20) & 0xFu; }
; __device__ __forceinline__ XcdBarrier xcd_barrier_post(unsigned* bar, volatile LAS unsigned* st) {
;     XcdBarrier b; b.bar = bar; b.x = xb_xcc_id(); b.st = st;
;     if (threadIdx.x == 0) (void)xb_add(&bar[XB_XCNT(b.x)], 1u);
;     return b;
; }
; __device__ __forceinline__ void xcd_barrier_complete(unsigned* bar, unsigned x, unsigned& nloc, unsigned& nx) {
;     const unsigned G = gridDim.x * gridDim.y * gridDim.z;
;     unsigned sum, cnt, mine, sp = 0u;
;     for (;;) {
;         sum = 0u; cnt = 0u; mine = 0u;
; #pragma unroll
;         for (unsigned j = 0; j < 16; ++j) { const unsigned c = xb_ld(&bar[XB_XCNT(j)]); sum += c; cnt += (c > 0u) ? 1u : 0u; mine = (j == x) ? c : mine; }
;         if (sum == G) break;
;         __builtin_amdgcn_s_sleep(1);
;         if ((++sp & 255u) == 0u) { if (xb_ld(&bar[XB_TMO])) break; if (sp > XB_SPIN_CAP) { atomicAdd(&bar[XB_TMO], 1u); break; } }
;     }
;     nloc = mine > 0u ? mine : 1u; nx = cnt > 0u ? cnt : 1u;
; }
; __device__ __forceinline__ void xcd_barrier(const XcdBarrier& b) {
;     asm volatile("s_waitcnt vmcnt(0)" ::: "memory");
;     __syncthreads();
;     if (threadIdx.x == 0) {
;         unsigned* bar = b.bar;
;         __builtin_amdgcn_s_waitcnt(0);
;         unsigned nloc = b.st[0], nx = b.st[1];
;         if (nloc == 0u) { xcd_barrier_complete(bar, b.x, nloc, nx); b.st[0] = nloc; b.st[1] = nx; }
; __global__ void __launch_bounds__(512, 2) mk_fwd(Args args) {
;     ...
;     XcdBarrier bar; bar.bar = (unsigned*)args.ws; bar.x = 0; bar.st = (volatile LAS unsigned*)(lds + LDS_BAR_OFF);
;     if (args.ph_hi - args.ph_lo > 1) {
;         if (threadIdx.x < 2) ((LAS unsigned*)(lds + LDS_BAR_OFF))[threadIdx.x] = 0u;
;         __syncthreads();
;         bar = xcd_barrier_post((unsigned*)args.ws, (volatile LAS unsigned*)(lds + LDS_BAR_OFF));
;     }
.LBB0_8:
	s_add_i32 s3, s58, 1
	s_add_u32 s0, s0, 0xe0
	v_writelane_b32 v253, s3, 48
	s_addc_u32 s1, s1, 0
	v_writelane_b32 v253, s0, 49
	v_and_b32_e32 v222, 0x3ff, v0
	v_and_b32_e32 v0, 0x3fffffff, v0
	v_writelane_b32 v253, s1, 50
	s_add_u32 s0, s56, 0x200
	s_addc_u32 s1, s57, 0
	s_add_u32 s46, s56, 0x1000
	s_addc_u32 s47, s57, 0
	s_add_u32 s22, s56, 0x1100
	s_addc_u32 s23, s57, 0
	s_add_u32 s78, s56, 0x1200
	s_addc_u32 s79, s57, 0
	s_add_u32 s40, s56, 0x1300
	s_addc_u32 s41, s57, 0
	v_writelane_b32 v253, s0, 51
	s_cmp_eq_u32 s2, 15
	s_mov_b32 s34, s58
	v_writelane_b32 v253, s1, 52
	s_cselect_b64 s[0:1], -1, 0
	v_writelane_b32 v253, s0, 53
	s_cmp_eq_u32 s2, 14
	v_mbcnt_lo_u32_b32 v2, -1, 0
	v_writelane_b32 v253, s1, 54
	s_cselect_b64 s[0:1], -1, 0
	v_writelane_b32 v253, s0, 55
	s_cmp_eq_u32 s2, 13
	v_mov_b32_e32 v1, 0
	v_writelane_b32 v253, s1, 56
	s_cselect_b64 s[0:1], -1, 0
	v_writelane_b32 v253, s0, 57
	s_cmp_eq_u32 s2, 12
	v_mov_b32_e32 v252, 1
	v_writelane_b32 v253, s1, 58
	s_cselect_b64 s[0:1], -1, 0
	v_writelane_b32 v253, s0, 59
	s_cmp_eq_u32 s2, 11
	v_mbcnt_hi_u32_b32 v224, -1, v2
	v_writelane_b32 v253, s1, 60
	s_cselect_b64 s[0:1], -1, 0
	v_writelane_b32 v253, s0, 61
	s_cmp_eq_u32 s2, 10
	v_mov_b32_e32 v225, 0x358637bd
	v_writelane_b32 v253, s1, 62
	s_cselect_b64 s[0:1], -1, 0
	v_writelane_b32 v253, s0, 63
	s_cmp_eq_u32 s2, 9
	v_mov_b32_e32 v226, 0x260
	v_writelane_b32 v254, s1, 0
	s_cselect_b64 s[0:1], -1, 0
	v_writelane_b32 v254, s0, 1
	s_cmp_eq_u32 s2, 8
	v_mov_b64_e32 v[186:187], 0x200
	v_writelane_b32 v254, s1, 2
	s_cselect_b64 s[0:1], -1, 0
	v_writelane_b32 v254, s0, 3
	s_cmp_eq_u32 s2, 7
	v_mov_b64_e32 v[188:189], 0x1ff
	v_writelane_b32 v254, s1, 4
	s_cselect_b64 s[0:1], -1, 0
	v_writelane_b32 v254, s0, 5
	s_cmp_eq_u32 s2, 6
	v_mov_b32_e32 v229, 0x600
	v_writelane_b32 v254, s1, 6
	s_cselect_b64 s[0:1], -1, 0
	v_writelane_b32 v254, s0, 7
	s_cmp_eq_u32 s2, 5
	v_mov_b32_e32 v230, 0x30000
	v_writelane_b32 v254, s1, 8
	s_cselect_b64 s[0:1], -1, 0
	v_writelane_b32 v254, s0, 9
	s_cmp_eq_u32 s2, 4
	v_mov_b32_e32 v231, 0xf149f2ca
	v_writelane_b32 v254, s1, 10
	s_cselect_b64 s[0:1], -1, 0
	v_writelane_b32 v254, s0, 11
	s_cmp_eq_u32 s2, 3
	v_mov_b64_e32 v[190:191], 0x100
	v_writelane_b32 v254, s1, 12
	s_cselect_b64 s[0:1], -1, 0
	v_writelane_b32 v254, s0, 13
	s_cmp_eq_u32 s2, 2
	v_mov_b64_e32 v[192:193], 0xff
	v_writelane_b32 v254, s1, 14
	s_cselect_b64 s[0:1], -1, 0
	v_writelane_b32 v254, s0, 15
	s_cmp_eq_u32 s2, 1
	v_mov_b32_e32 v238, 0xffffce00
	v_writelane_b32 v254, s1, 16
	s_cselect_b64 s[0:1], -1, 0
	v_writelane_b32 v254, s0, 17
	s_cmp_eq_u32 s2, 0
	v_mov_b32_e32 v239, 0xffffc400
	v_writelane_b32 v254, s1, 18
	s_cselect_b64 s[0:1], -1, 0
	v_writelane_b32 v254, s0, 19
	v_mov_b32_e32 v240, 0xffffba00
	v_mov_b32_e32 v241, 0xffffb000
	v_writelane_b32 v254, s1, 20
	s_lshl_b32 s0, s2, 8
	s_add_u32 s0, s56, s0
	s_addc_u32 s1, s57, 0
	s_add_u32 s2, s0, 0x1400
	s_addc_u32 s3, s1, 0
	v_writelane_b32 v254, s2, 21
	s_add_u32 s0, s0, 0x2400
	s_addc_u32 s1, s1, 0
	v_writelane_b32 v254, s3, 22
	v_writelane_b32 v254, s0, 23
	v_mov_b32_e32 v242, 0xffffa600
	v_mov_b32_e32 v243, 0xffff9c00
	v_writelane_b32 v254, s1, 24
	s_add_u32 s0, s56, 0x3400
	s_addc_u32 s1, s57, 0
	v_writelane_b32 v254, s0, 25
	v_mov_b32_e32 v244, 0xffff9200
	v_mov_b32_e32 v245, 0xffff8800
	v_writelane_b32 v254, s1, 26
	s_add_u32 s0, s56, 0x3500
	s_addc_u32 s1, s57, 0
	v_writelane_b32 v254, s0, 27
	v_mov_b32_e32 v223, 0xffff7e00
	v_mov_b32_e32 v228, 0xffff7400
	v_writelane_b32 v254, s1, 28
	v_readlane_b32 s0, v253, 32
	v_readlane_b32 s4, v253, 36
	v_readlane_b32 s5, v253, 37
	v_readlane_b32 s10, v253, 42
	v_readlane_b32 s11, v253, 43
	v_readlane_b32 s12, v253, 44
	v_readlane_b32 s13, v253, 45
	v_readlane_b32 s14, v253, 46
	v_readlane_b32 s15, v253, 47
	v_readlane_b32 s1, v253, 33
	s_mov_b64 s[4:5], s[22:23]
	s_cmp_lg_u64 s[10:11], 0
	v_readlane_b32 s12, v253, 16
	s_cselect_b64 s[0:1], -1, 0
	v_readlane_b32 s13, v253, 17
	v_readlane_b32 s14, v253, 18
	v_readlane_b32 s15, v253, 19
	v_readlane_b32 s16, v253, 20
	v_readlane_b32 s17, v253, 21
	v_readlane_b32 s18, v253, 22
	v_readlane_b32 s19, v253, 23
	v_readlane_b32 s20, v253, 24
	v_readlane_b32 s21, v253, 25
	v_readlane_b32 s22, v253, 26
	v_readlane_b32 s23, v253, 27
	v_readlane_b32 s24, v253, 28
	v_readlane_b32 s25, v253, 29
	v_readlane_b32 s26, v253, 30
	v_readlane_b32 s27, v253, 31
	v_writelane_b32 v254, s0, 29
	s_cmp_lg_u64 s[12:13], 0
	v_readlane_b32 s12, v253, 0
	v_writelane_b32 v254, s1, 30
	s_cselect_b64 s[0:1], -1, 0
	v_readlane_b32 s24, v253, 12
	v_readlane_b32 s25, v253, 13
	v_writelane_b32 v254, s0, 31
	s_cmp_lg_u64 s[24:25], 0
	v_readlane_b32 s14, v253, 2
	v_writelane_b32 v254, s1, 32
	v_readlane_b32 s15, v253, 3
	s_cselect_b64 s[0:1], -1, 0
	v_writelane_b32 v254, s0, 33
	s_cmp_lg_u64 s[14:15], 0
	v_readlane_b32 s13, v253, 1
	v_writelane_b32 v254, s1, 34
	s_cselect_b64 s[0:1], -1, 0
	v_writelane_b32 v254, s0, 35
	v_readlane_b32 s3, v253, 35
	v_readlane_b32 s22, v253, 10
	v_writelane_b32 v254, s1, 36
	s_add_u32 s0, s12, 0xc00
	v_writelane_b32 v254, s0, 37
	s_addc_u32 s0, s13, 0
	v_writelane_b32 v254, s0, 38
	s_add_i32 s0, 0, 0x20100
	v_writelane_b32 v254, s0, 39
	s_add_i32 s0, 0, 0x20104
	v_writelane_b32 v254, s0, 40
	v_cmp_eq_u32_e64 s[0:1], 0, v222
	v_readlane_b32 s23, v253, 11
	v_readlane_b32 s26, v253, 14
	v_writelane_b32 v254, s0, 41
	v_readlane_b32 s27, v253, 15
	v_mov_b32_e32 v227, 0xffff6a00
	v_writelane_b32 v254, s1, 42
	v_cmp_eq_u32_e64 s[0:1], 0, v0
	v_mov_b32_e32 v195, 0x7f800000
	v_mov_b32_e32 v194, 0x3f317218
	v_writelane_b32 v254, s0, 43
	s_movk_i32 s64, 0x2000
	s_movk_i32 s66, 0x4000
	v_writelane_b32 v254, s1, 44
	v_writelane_b32 v254, s62, 45
	v_writelane_b32 v254, s52, 46
	s_movk_i32 s70, 0x6000
	s_movk_i32 s73, 0x60
	v_writelane_b32 v254, s53, 47
	v_writelane_b32 v254, s54, 48
	v_writelane_b32 v254, s55, 49
	v_writelane_b32 v254, s56, 50
	v_writelane_b32 v254, s57, 51
	v_writelane_b32 v254, s58, 52
	v_writelane_b32 v254, s59, 53
	v_writelane_b32 v254, s46, 54
	s_movk_i32 s33, 0x1800
	s_movk_i32 s75, 0x5000
	v_writelane_b32 v254, s47, 55
	v_writelane_b32 v254, s4, 56
	s_movk_i32 s83, 0x600
	s_mov_b32 s63, 0x2aaaaaab
	v_writelane_b32 v254, s5, 57
	v_writelane_b32 v254, s78, 58
	s_movk_i32 s65, 0xd0
	s_mov_b32 s71, 0x30000
	v_writelane_b32 v254, s79, 59
	v_writelane_b32 v254, s40, 60
	s_mov_b32 s23, 0x41000000
	s_mov_b32 s3, 0xf800000
	s_mov_b32 s49, 0
	s_mov_b64 s[26:27], 0x80
	s_mov_b32 s22, 0x3e16c740
	v_writelane_b32 v254, s41, 61
	v_readlane_b32 s2, v253, 34
	v_readlane_b32 s6, v253, 38
	v_readlane_b32 s7, v253, 39
	v_readlane_b32 s8, v253, 40
	v_readlane_b32 s9, v253, 41
	v_readlane_b32 s16, v253, 4
	v_readlane_b32 s17, v253, 5
	v_readlane_b32 s18, v253, 6
	v_readlane_b32 s19, v253, 7
	v_readlane_b32 s20, v253, 8
	v_readlane_b32 s21, v253, 9
	v_writelane_b32 v255, 0, 12
	s_branch .LBB0_10
; __global__ void __launch_bounds__(512, 2) mk_fwd(Args args) {
;     ...
;     for (int ph = args.ph_lo; ph < args.ph_hi; ++ph) {
;         if (ph == args.ph_lo + 1) cg::this_grid().sync();
;         else if (ph > args.ph_lo) xcd_barrier(bar);
;         const int l = ph / PH_PER_LAYER; int p = 0, rep = ph % PH_PER_LAYER, nrep = 1;
;         for (; p < NPH; ++p) { nrep = 1 + ((REP_MASK >> p) & 1); if (rep < nrep) break; rep -= nrep; }
.LBB0_9:
	v_readlane_b32 s0, v255, 12
	s_cmp_eq_u32 s0, 1
	s_cbranch_scc1 .Lwp_done
	s_cmp_ge_i32 s34, 36
	s_cbranch_scc1 .Lwp_adv
	s_mul_hi_i32 s0, s34, 0x38e38e39
	s_lshr_b32 s1, s0, 31
	s_ashr_i32 s0, s0, 1
	s_add_i32 s0, s0, s1
	s_cmp_eq_u32 s0, 0
	s_cbranch_scc1 .Lwp_adv
	s_mul_i32 s0, s0, 9
	s_sub_i32 s0, s34, s0
	s_cmp_lg_u32 s0, 1
	s_cbranch_scc1 .Lwp_adv
	s_cmpk_lt_i32 s62, 0x80
	s_cbranch_scc1 .Lwp_adv
	v_readlane_b32 s0, v253, 49
	v_readlane_b32 s1, v253, 50
	s_nop 4
	s_load_dword s0, s[0:1], 0x0
	s_waitcnt lgkmcnt(0)
	s_cmpk_lg_i32 s0, 0x100
	s_cbranch_scc1 .Lwp_adv
	s_mov_b32 s0, 1
	v_writelane_b32 v255, s0, 12
	s_sub_i32 s34, s34, 1
	s_waitcnt vmcnt(0) lgkmcnt(0)
	s_barrier
	s_branch .LBB0_75
.Lwp_done:
	s_mov_b32 s0, 0
	v_writelane_b32 v255, s0, 12
	s_add_i32 s34, s34, 1

; #define LAS __attribute__((address_space(3)))
; __device__ __forceinline__ void wprep_phase(const WArgs& a, LAS float* scr, int gw, int NGW, int lane, int gtid, int NGT) {
;     constexpr int I0 = 16 * 133, I1 = 6 * 24, I2 = 4 * 32, I3 = 8 * 32, I4 = 4 * 32, I5 = 16 * 32, I6 = 16 * 128, I7 = 64 * 32;
;     constexpr int NIT = I0 + I1 + I2 + I3 + I4 + I5 + I6 + I7;
;     for (int it = gw; it < NIT; it += NGW) {
;         int r = it;
;         if (r < I0) { const int kb = r / 133, nb = r % 133; tr_item(a.w_in, IN_COLS, 64 * kb, 32 * nb, a.W + WO_IN, 1024, win_dst(32 * nb), scr, lane, a.g_mix); continue; } r -= I0;
; __global__ void __launch_bounds__(512, 2) mk_fwd(Args args) {
;     ...
;             PHASE_IDS; WArgs wa; wa.w_in = args.in[2] + (size_t)l * 1024 * IN_COLS; wa.w_q = args.in[7] + (size_t)l * 384 * 768; wa.w_kv = args.in[9] + (size_t)l * 256 * 1024;
;             wa.w_mlao = args.in[10] + (size_t)l * 512 * 1024; wa.w_lrup = args.in[18] + (size_t)l * 256 * 1024; wa.w_out = args.in[20] + (size_t)l * 1024 * 1024;
;             wa.w_ff1 = args.in[22] + (size_t)l * 1024 * 4096; wa.w_ff2 = args.in[23] + (size_t)l * 4096 * 1024; wa.w_pgrp = args.in[3] + (size_t)l * 4 * 64 * 64;
;             wa.pscale = args.in[4] + (size_t)l * 256; wa.w_pproj = args.in[5] + (size_t)l * 256 * 1024; wa.w_a = args.in[13] + (size_t)l * 4 * 64 * 64; wa.w_x = args.in[15] + (size_t)l * 4 * 64 * 64; wa.W = Wb; wa.lam = args.in[17] + l * 256; wa.cdec = cdec; wa.g_mix = args.in[1] + l * DM; wa.g_ffn = args.in[21] + l * DM; wa.g_q = args.in[6] + l * 384; wa.g_kv = args.in[8] + l * 256;
;             wprep_phase(wa, (LAS float*)(lds + wave * 16384), gw, NGW, lane, gtid, NGT);
.LBB0_567:
	s_andn2_b64 vcc, exec, s[0:1]
	s_cbranch_vccnz .LBB0_797
	s_add_u32 s24, s50, 0x200000
	s_addc_u32 s25, s51, 0
	s_cmp_lg_u32 s18, 1
	s_mov_b64 s[0:1], -1
	s_cbranch_scc0 .LBB0_729
	v_mov_b32_e32 v81, v222
	s_lshl_b32 s55, s2, 3
	v_readfirstlane_b32 s0, v81
	s_ashr_i32 s54, s0, 6
	s_lshl_b32 s30, s76, 8
	s_mov_b32 s96, s34
	s_add_i32 s34, s54, s55
	v_readlane_b32 s0, v255, 12
	s_cmp_eq_u32 s0, 1
	s_cbranch_scc1 .Lwp_e1
	s_mov_b32 s0, 0
	s_cmpk_lg_i32 s35, 0x100
	s_cbranch_scc1 .Lwp_e0
	s_cmp_eq_u32 s76, 0
	s_cbranch_scc1 .Lwp_e0
	s_mov_b32 s0, 2
.Lwp_e0:
	v_writelane_b32 v255, s0, 12
.Lwp_e1:
	s_ashr_i32 s77, s76, 31
	s_ashr_i32 s31, s30, 31
	s_cmpk_gt_i32 s34, 0x1cdf
	v_and_b32_e32 v80, 63, v81
	s_cbranch_scc1 .LBB0_698
	s_lshl_b32 s0, s76, 10
	s_ashr_i32 s1, s0, 31
	s_mov_b64 s[4:5], s[80:81]
	v_readlane_b32 s80, v253, 0
	s_lshl_b64 s[0:1], s[0:1], 2
	v_readlane_b32 s81, v253, 1
	v_readlane_b32 s82, v253, 2
	v_readlane_b32 s83, v253, 3
	s_mov_b64 s[80:81], s[4:5]
	s_add_u32 s36, s82, s0
	v_readlane_b32 s4, v253, 32
	s_addc_u32 s37, s83, s1
	v_readlane_b32 s14, v253, 42
	v_readlane_b32 s15, v253, 43
	s_add_u32 s40, s14, s0
	s_mul_i32 s0, s76, 0x180
	s_addc_u32 s41, s15, s1
	s_ashr_i32 s1, s0, 31
	v_readlane_b32 s92, v253, 12
	s_lshl_b64 s[0:1], s[0:1], 2
	v_readlane_b32 s93, v253, 13
	v_readlane_b32 s5, v253, 33
	s_add_u32 s42, s92, s0
	s_addc_u32 s43, s93, s1
	s_lshl_b64 s[0:1], s[30:31], 2
	s_mov_b64 s[4:5], s[76:77]
	v_readlane_b32 s64, v253, 16
	v_readlane_b32 s65, v253, 17
	s_add_u32 s52, s64, s0
	v_readlane_b32 s18, v253, 46
	v_readlane_b32 s76, v253, 28
	v_readlane_b32 s77, v253, 29
	s_addc_u32 s53, s65, s1
	s_lshl_b64 s[0:1], s[4:5], 24
	v_readlane_b32 s19, v253, 47
	s_mov_b64 s[76:77], s[4:5]
	s_add_u32 s4, s18, s0
	v_readlane_b32 s16, v253, 44
	s_addc_u32 s5, s19, s1
	v_readlane_b32 s17, v253, 45
	s_add_u32 s0, s16, s0
	v_readlane_b32 s12, v253, 40
	s_addc_u32 s1, s17, s1
	s_lshl_b64 s[20:21], s[76:77], 22
	v_readlane_b32 s13, v253, 41
	s_add_u32 s20, s12, s20
	v_readlane_b32 s8, v253, 36
	s_addc_u32 s21, s13, s21
	s_lshl_b64 s[38:39], s[76:77], 20
	v_readlane_b32 s9, v253, 37
	s_add_u32 s44, s8, s38
	v_readlane_b32 s68, v253, 20
	s_addc_u32 s45, s9, s39
	s_lshl_b64 s[46:47], s[76:77], 21
	v_readlane_b32 s69, v253, 21
	s_add_u32 s46, s68, s46
	v_readlane_b32 s66, v253, 18
	s_addc_u32 s47, s69, s47
	v_lshlrev_b32_e32 v0, 4, v80
	v_readlane_b32 s67, v253, 19
	s_add_u32 s38, s66, s38
	v_and_b32_e32 v0, 0x70, v0
	v_readlane_b32 s94, v253, 14
	s_addc_u32 s39, s67, s39
	s_waitcnt vmcnt(0) lgkmcnt(0)
	v_lshl_add_u64 v[40:41], s[0:1], 0, v[0:1]
	s_mul_i32 s0, s76, 0x120000
	v_readlane_b32 s95, v253, 15
	s_mul_hi_i32 s15, s76, 0x120000
	s_add_u32 s0, s94, s0
	v_readlane_b32 s84, v253, 4
	s_addc_u32 s1, s95, s15
	s_mul_i32 s16, s76, 0x10a0000
	v_readlane_b32 s85, v253, 5
	s_mul_hi_i32 s15, s76, 0x10a0000
	s_add_u32 s16, s84, s16
	v_lshlrev_b32_e32 v2, 3, v80
	s_addc_u32 s17, s85, s15
	s_lshl_b32 s15, s54, 14
	v_lshrrev_b32_e32 v44, 3, v80
	v_and_b32_e32 v2, 56, v2
	s_add_i32 s15, s15, 0
	v_mul_u32_u24_e32 v3, 0x84, v2
	v_lshlrev_b32_e32 v4, 2, v44
	v_lshl_add_u64 v[38:39], s[4:5], 0, v[0:1]
	v_lshl_add_u64 v[42:43], s[20:21], 0, v[0:1]
	v_add_u32_e32 v82, s15, v0
	v_add3_u32 v87, s15, v3, v4
	v_or_b32_e32 v3, 32, v44
	v_lshl_add_u64 v[46:47], s[44:45], 0, v[0:1]
	v_lshl_add_u64 v[48:49], s[46:47], 0, v[0:1]
	v_lshl_add_u64 v[50:51], s[38:39], 0, v[0:1]
	v_lshl_add_u64 v[52:53], s[0:1], 0, v[0:1]
	v_lshl_add_u64 v[54:55], s[16:17], 0, v[0:1]
	v_lshlrev_b32_e32 v0, 1, v2
	v_mul_u32_u24_e32 v88, 0x84, v3
	v_lshl_add_u64 v[2:3], s[50:51], 0, v[0:1]
	s_mov_b64 s[0:1], 0x17d0000
	v_lshl_add_u64 v[58:59], v[2:3], 0, s[0:1]
	s_mov_b64 s[0:1], 0xfd0000
	v_lshl_add_u64 v[60:61], v[2:3], 0, s[0:1]
	s_mov_b64 s[0:1], 0xdd0000
	v_lshl_add_u64 v[62:63], v[2:3], 0, s[0:1]
	s_mov_b64 s[0:1], 0xbd0600
	v_lshl_add_u64 v[64:65], v[2:3], 0, s[0:1]
	s_mov_b64 s[0:1], 0xbd0200
	v_lshl_add_u64 v[66:67], v[2:3], 0, s[0:1]
	s_mov_b64 s[0:1], 0xb50000
	v_readlane_b32 s78, v253, 30
	v_readlane_b32 s79, v253, 31
	v_lshl_add_u64 v[68:69], v[2:3], 0, s[0:1]
	s_mov_b64 s[0:1], 0xb10000
	v_readlane_b32 s70, v253, 22
	v_readlane_b32 s71, v253, 23
	v_readlane_b32 s73, v253, 25
	v_readlane_b32 s75, v253, 27
	v_readlane_b32 s78, v254, 58
	v_readlane_b32 s94, v255, 0
	v_lshl_add_u64 v[70:71], v[2:3], 0, s[0:1]
	s_mov_b64 s[0:1], 0xa80000
	s_movk_i32 s83, 0x600
	s_mov_b32 s71, 0x30000
	s_movk_i32 s75, 0x5000
	s_movk_i32 s73, 0x60
	s_movk_i32 s70, 0x6000
	v_readlane_b32 s79, v254, 59
	s_movk_i32 s64, 0x2000
	s_movk_i32 s65, 0xd0
	s_mov_b32 s63, 0x2aaaaaab
	s_movk_i32 s66, 0x4000
	v_mul_u32_u24_e32 v83, 0x84, v44
	v_or_b32_e32 v84, 8, v44
	v_or_b32_e32 v85, 16, v44
	v_or_b32_e32 v86, 24, v44
	v_lshl_add_u64 v[56:57], s[24:25], 0, v[0:1]
	v_lshl_add_u64 v[72:73], v[2:3], 0, s[0:1]
	v_mov_b32_e32 v45, v1
	v_readlane_b32 s0, v255, 12
	s_cmp_eq_u32 s0, 1
	s_cbranch_scc0 .Lwp_norm
	s_add_i32 s34, s34, 0xc00
	s_lshr_b32 s94, s94, 1
.Lwp_norm:
	s_lshl_b32 s15, s34, 5
	s_lshl_b32 s16, s94, 5
	s_lshl_b32 s17, s34, 1
	s_lshl_b32 s19, s94, 1
	s_lshl_b32 s44, s34, 4
	s_lshl_b32 s45, s94, 4
	s_mov_b32 s46, s34
	v_readlane_b32 s86, v253, 6
	v_readlane_b32 s87, v253, 7
	v_readlane_b32 s88, v253, 8
	v_readlane_b32 s89, v253, 9
	v_readlane_b32 s90, v253, 10
	v_readlane_b32 s91, v253, 11
	v_readlane_b32 s6, v253, 34
	v_readlane_b32 s7, v253, 35
	v_readlane_b32 s10, v253, 38
	v_readlane_b32 s11, v253, 39
	v_readlane_b32 s72, v253, 24
	v_readlane_b32 s74, v253, 26
	v_readlane_b32 s95, v255, 1
	s_branch .LBB0_574

; __device__ __forceinline__ void wprep_phase(const WArgs& a, LAS float* scr, int gw, int NGW, int lane, int gtid, int NGT) {
;     ...
;     for (int it = gw; it < NIT; it += NGW) {
;         int r = it;
.LBB0_573:
	s_add_i32 s46, s46, s94
	s_add_i32 s15, s15, s16
	s_add_i32 s17, s17, s19
	s_add_i32 s44, s44, s45
	s_cmpk_gt_i32 s46, 0x1cdf
	s_cbranch_scc1 .LBB0_698
	s_cmpk_lt_i32 s46, 0x1000
	s_cbranch_scc1 .LBB0_574
	v_readlane_b32 s0, v255, 12
	s_cmp_eq_u32 s0, 2
	s_cbranch_scc1 .LBB0_698

; __device__ __forceinline__ void wprep_phase(const WArgs& a, LAS float* scr, int gw, int NGW, int lane, int gtid, int NGT) {
;     ...
;     for (int e = gtid; e < 256; e += NGT) a.cdec[e] = -8.0f * log1pf(expf(-a.lam[e]));
;     for (int e = gtid; e < 1024 * 256; e += NGT) { const int n = e & 1023, k = e >> 10, gI = k >> 6, cI = k & 63;
.LBB0_698:
	v_readlane_b32 s0, v255, 12
	s_cmp_eq_u32 s0, 1
	s_cbranch_scc0 .Lwp_x
	s_sub_i32 s34, s34, 0xc00
.Lwp_x:
	v_readlane_b32 s94, v255, 0
	s_waitcnt vmcnt(0) lgkmcnt(0)
	v_lshl_add_u32 v2, s2, 9, v81
	s_movk_i32 s0, 0x100
	s_lshl_b32 s36, s35, 9
	v_cmp_gt_i32_e32 vcc, s0, v2
	s_and_saveexec_b64 s[20:21], vcc
	s_mov_b32 s48, 0x7f800000
	s_mov_b32 s52, 0x3f2aaaab
	s_mov_b32 s53, 0x3f317218
	s_cbranch_execz .LBB0_701
	v_readlane_b32 s4, v253, 32
	s_lshl_b64 s[0:1], s[30:31], 2
	v_readlane_b32 s6, v253, 34
	v_readlane_b32 s7, v253, 35
	s_add_u32 s30, s6, s0
	s_addc_u32 s31, s7, s1
	v_ashrrev_i32_e32 v3, 31, v2
	s_ashr_i32 s37, s36, 31
	v_lshlrev_b64 v[4:5], 2, v[2:3]
	s_lshl_b64 s[38:39], s[36:37], 2
	s_mov_b64 s[40:41], 0
	v_mov_b32_e32 v0, v2
	v_readlane_b32 s5, v253, 33
	v_readlane_b32 s8, v253, 36
	v_readlane_b32 s9, v253, 37
	v_readlane_b32 s10, v253, 38
	v_readlane_b32 s11, v253, 39
	v_readlane_b32 s12, v253, 40
	v_readlane_b32 s13, v253, 41
	v_readlane_b32 s14, v253, 42
	v_readlane_b32 s15, v253, 43
	v_readlane_b32 s16, v253, 44
	v_readlane_b32 s17, v253, 45
	v_readlane_b32 s18, v253, 46
	v_readlane_b32 s19, v253, 47
